# packed f32 adds (v_pk_add_f32) for the per-tile exponential sums in the attention loops: 21-22 VALU instead of 33
# baseline (speedup 1.0000x reference)
.LBB0_1200:
	v_exp_f32_e32 v207, v82
	v_exp_f32_e32 v208, v83
	v_exp_f32_e32 v209, v84
	v_add_u32_e32 v1, s56, v201
	v_exp_f32_e32 v211, v86
	v_add3_u32 v1, v1, v204, v205
	v_exp_f32_e32 v224, v88
	v_exp_f32_e32 v226, v87
	v_exp_f32_e32 v225, v89
	v_exp_f32_e32 v227, v85
	ds_read_b64_tr_b16 v[86:87], v1 offset:25600
	ds_read_b64_tr_b16 v[88:89], v1 offset:28160
	v_cvt_pk_bf16_f32 v84, v211, v226
	v_cvt_pk_bf16_f32 v85, v224, v225
	v_cvt_pk_bf16_f32 v83, v209, v227
	v_cvt_pk_bf16_f32 v82, v207, v208
	ds_read_b64_tr_b16 v[212:213], v1 offset:25664
	ds_read_b64_tr_b16 v[216:217], v1 offset:25728
	ds_read_b64_tr_b16 v[220:221], v1 offset:25792
	ds_read_b64_tr_b16 v[214:215], v1 offset:28224
	ds_read_b64_tr_b16 v[218:219], v1 offset:28288
	ds_read_b64_tr_b16 v[222:223], v1 offset:28352
	s_waitcnt lgkmcnt(6)
	v_mfma_f32_32x32x16_bf16 v[50:65], v[86:89], v[82:85], v[50:65]
	v_exp_f32_e32 v228, v90
	v_exp_f32_e32 v229, v91
	v_exp_f32_e32 v230, v92
	v_exp_f32_e32 v231, v94
	s_waitcnt lgkmcnt(1)
	v_mfma_f32_32x32x16_bf16 v[18:33], v[216:219], v[82:85], v[18:33]
	v_exp_f32_e32 v216, v96
	v_exp_f32_e32 v217, v97
	v_exp_f32_e32 v218, v95
	v_exp_f32_e32 v219, v93
	ds_read_b64_tr_b16 v[86:87], v1 offset:30720
	ds_read_b64_tr_b16 v[88:89], v1 offset:33280
	v_mov_b32_e32 v254, v207
	v_mfma_f32_32x32x16_bf16 v[34:49], v[212:215], v[82:85], v[34:49]
	ds_read_b64_tr_b16 v[90:91], v1 offset:30784
	ds_read_b64_tr_b16 v[94:95], v1 offset:30848
	ds_read_b64_tr_b16 v[212:213], v1 offset:30912
	ds_read_b64_tr_b16 v[92:93], v1 offset:33344
	ds_read_b64_tr_b16 v[96:97], v1 offset:33408
	ds_read_b64_tr_b16 v[214:215], v1 offset:33472
	s_add_i32 s55, s55, 64
	v_lshl_add_u64 v[174:175], v[174:175], 0, s[14:15]
	s_cmp_eq_u32 s2, s11
	v_lshl_add_u64 v[176:177], v[176:177], 0, s[18:19]
	s_waitcnt lgkmcnt(8)
	v_mfma_f32_32x32x16_bf16 v[2:17], v[220:223], v[82:85], v[2:17]
	v_cvt_pk_bf16_f32 v85, v216, v217
	v_cvt_pk_bf16_f32 v84, v231, v218
	v_cvt_pk_bf16_f32 v83, v230, v219
	v_cvt_pk_bf16_f32 v82, v228, v229
	s_waitcnt lgkmcnt(6)
	s_nop 0
	v_mfma_f32_32x32x16_bf16 v[50:65], v[86:89], v[82:85], v[50:65]
	v_pk_add_f32 v[252:253], v[208:209], 0 op_sel_hi:[1,0]
	v_exp_f32_e32 v208, v66
	v_exp_f32_e32 v209, v67
	v_add_f32_e32 v254, v211, v254
	v_exp_f32_e32 v211, v68
	v_exp_f32_e32 v220, v70
	s_waitcnt lgkmcnt(1)
	v_mfma_f32_32x32x16_bf16 v[18:33], v[94:97], v[82:85], v[18:33]
	v_exp_f32_e32 v94, v72
	v_exp_f32_e32 v95, v73
	v_exp_f32_e32 v96, v71
	v_exp_f32_e32 v97, v69
	ds_read_b64_tr_b16 v[70:71], v1 offset:35840
	ds_read_b64_tr_b16 v[72:73], v1 offset:38400
	v_pk_add_f32 v[252:253], v[252:253], v[226:227]
	v_cvt_pk_bf16_f32 v69, v94, v95
	v_cvt_pk_bf16_f32 v68, v220, v96
	v_cvt_pk_bf16_f32 v67, v211, v97
	v_cvt_pk_bf16_f32 v66, v208, v209
	v_mfma_f32_32x32x16_bf16 v[34:49], v[90:93], v[82:85], v[34:49]
	s_waitcnt lgkmcnt(0)
	v_mfma_f32_32x32x16_bf16 v[50:65], v[70:73], v[66:69], v[50:65]
	v_pk_add_f32 v[252:253], v[252:253], v[224:225]
	v_pk_add_f32 v[252:253], v[252:253], v[228:229]
	v_mfma_f32_32x32x16_bf16 v[2:17], v[212:215], v[82:85], v[2:17]
	ds_read_b64_tr_b16 v[82:83], v1 offset:35904
	ds_read_b64_tr_b16 v[86:87], v1 offset:35968
	ds_read_b64_tr_b16 v[90:91], v1 offset:36032
	ds_read_b64_tr_b16 v[84:85], v1 offset:38464
	ds_read_b64_tr_b16 v[88:89], v1 offset:38528
	ds_read_b64_tr_b16 v[92:93], v1 offset:38592
	v_exp_f32_e32 v212, v74
	v_exp_f32_e32 v213, v75
	v_exp_f32_e32 v214, v76
	v_exp_f32_e32 v215, v78
	s_waitcnt lgkmcnt(1)
	v_mfma_f32_32x32x16_bf16 v[18:33], v[86:89], v[66:69], v[18:33]
	v_exp_f32_e32 v86, v80
	v_exp_f32_e32 v87, v81
	v_exp_f32_e32 v88, v79
	v_exp_f32_e32 v89, v77
	ds_read_b64_tr_b16 v[70:71], v1 offset:40960
	ds_read_b64_tr_b16 v[72:73], v1 offset:43520
	v_mfma_f32_32x32x16_bf16 v[34:49], v[82:85], v[66:69], v[34:49]
	ds_read_b64_tr_b16 v[74:75], v1 offset:41024
	ds_read_b64_tr_b16 v[78:79], v1 offset:41088
	ds_read_b64_tr_b16 v[82:83], v1 offset:41152
	ds_read_b64_tr_b16 v[76:77], v1 offset:43584
	ds_read_b64_tr_b16 v[80:81], v1 offset:43648
	ds_read_b64_tr_b16 v[84:85], v1 offset:43712
	v_pk_add_f32 v[252:253], v[252:253], v[230:231]
	v_pk_add_f32 v[252:253], v[252:253], v[218:219]
	v_pk_add_f32 v[252:253], v[252:253], v[216:217]
	s_waitcnt lgkmcnt(8)
	v_mfma_f32_32x32x16_bf16 v[2:17], v[90:93], v[66:69], v[2:17]
	v_pk_add_f32 v[252:253], v[252:253], v[208:209]
	v_add_f32_e32 v254, v211, v254
	v_add_f32_e32 v254, v220, v254
	v_pk_add_f32 v[252:253], v[252:253], v[96:97]
	v_pk_add_f32 v[252:253], v[252:253], v[94:95]
	v_cvt_pk_bf16_f32 v69, v86, v87
	v_cvt_pk_bf16_f32 v68, v215, v88
	v_cvt_pk_bf16_f32 v67, v214, v89
	v_cvt_pk_bf16_f32 v66, v212, v213
	v_pk_add_f32 v[252:253], v[252:253], v[212:213]
	s_waitcnt lgkmcnt(6)
	v_mfma_f32_32x32x16_bf16 v[50:65], v[70:73], v[66:69], v[50:65]
	v_pk_add_f32 v[252:253], v[252:253], v[214:215]
	v_pk_add_f32 v[252:253], v[252:253], v[88:89]
	v_pk_add_f32 v[252:253], v[252:253], v[86:87]
	v_add_f32_e32 v254, v252, v254
	v_add_f32_e32 v254, v253, v254
	v_add_f32_e32 v186, v186, v254
	s_waitcnt lgkmcnt(2)
	v_mfma_f32_32x32x16_bf16 v[34:49], v[74:77], v[66:69], v[34:49]
	s_waitcnt lgkmcnt(1)
	v_mfma_f32_32x32x16_bf16 v[18:33], v[78:81], v[66:69], v[18:33]
	s_waitcnt lgkmcnt(0)
	v_mfma_f32_32x32x16_bf16 v[2:17], v[82:85], v[66:69], v[2:17]
	s_cbranch_scc1 .LBB0_1207

.LBB0_2144:
	v_exp_f32_e32 v0, v50
	v_exp_f32_e32 v51, v51
	v_exp_f32_e32 v52, v52
	v_add_u32_e32 v50, s39, v109
	v_exp_f32_e32 v53, v53
	v_add3_u32 v145, v50, v143, v144
	v_mov_b32_e32 v234, v0
	v_exp_f32_e32 v54, v54
	v_add_f32_e32 v234, v51, v234
	v_exp_f32_e32 v55, v55
	v_exp_f32_e32 v56, v56
	v_pk_add_f32 v[232:233], v[52:53], 0 op_sel_hi:[1,0]
	v_exp_f32_e32 v57, v57
	v_exp_f32_e32 v58, v58
	v_pk_add_f32 v[232:233], v[232:233], v[54:55]
	v_exp_f32_e32 v59, v59
	v_exp_f32_e32 v60, v60
	v_pk_add_f32 v[232:233], v[232:233], v[56:57]
	v_exp_f32_e32 v61, v61
	v_exp_f32_e32 v62, v62
	v_pk_add_f32 v[232:233], v[232:233], v[58:59]
	v_exp_f32_e32 v63, v63
	v_exp_f32_e32 v64, v64
	v_pk_add_f32 v[232:233], v[232:233], v[60:61]
	v_exp_f32_e32 v65, v65
	v_exp_f32_e32 v146, v34
	v_pk_add_f32 v[232:233], v[232:233], v[62:63]
	v_exp_f32_e32 v147, v35
	v_exp_f32_e32 v148, v36
	v_pk_add_f32 v[232:233], v[232:233], v[64:65]
	v_exp_f32_e32 v149, v37
	v_exp_f32_e32 v150, v38
	v_pk_add_f32 v[232:233], v[232:233], v[146:147]
	v_pk_add_f32 v[232:233], v[232:233], v[148:149]
	v_add_f32_e32 v234, v150, v234
	v_exp_f32_e32 v152, v39
	v_exp_f32_e32 v153, v40
	v_exp_f32_e32 v154, v41
	ds_read_b64_tr_b16 v[34:35], v145 offset:9216
	ds_read_b64_tr_b16 v[36:37], v145 offset:10752
	v_exp_f32_e32 v155, v42
	v_cvt_pk_bf16_f32 v39, v52, v53
	v_cvt_pk_bf16_f32 v38, v0, v51
	ds_read_b64_tr_b16 v[52:53], v145 offset:10816
	ds_read_b64_tr_b16 v[50:51], v145 offset:9280
	v_cvt_pk_bf16_f32 v41, v56, v57
	v_cvt_pk_bf16_f32 v40, v54, v55
	v_mov_b32_e32 v54, v43
	s_waitcnt lgkmcnt(2)
	v_mfma_f32_32x32x16_bf16 v[2:17], v[34:37], v[38:41], v[2:17]
	ds_read_b64_tr_b16 v[34:35], v145 offset:12288
	ds_read_b64_tr_b16 v[36:37], v145 offset:13824
	v_exp_f32_e32 v55, v44
	v_exp_f32_e32 v47, v47
	v_pk_add_f32 v[232:233], v[232:233], v[152:153]
	s_waitcnt lgkmcnt(2)
	v_mfma_f32_32x32x16_bf16 v[18:33], v[50:53], v[38:41], v[18:33]
	ds_read_b64_tr_b16 v[52:53], v145 offset:13888
	ds_read_b64_tr_b16 v[50:51], v145 offset:12352
	v_cvt_pk_bf16_f32 v41, v64, v65
	v_cvt_pk_bf16_f32 v40, v62, v63
	v_cvt_pk_bf16_f32 v39, v60, v61
	v_cvt_pk_bf16_f32 v38, v58, v59
	v_pk_add_f32 v[232:233], v[232:233], v[154:155]
	s_add_i32 s37, s37, 64
	s_waitcnt lgkmcnt(2)
	v_mfma_f32_32x32x16_bf16 v[2:17], v[34:37], v[38:41], v[2:17]
	v_exp_f32_e32 v56, v45
	v_exp_f32_e32 v46, v46
	ds_read_b64_tr_b16 v[34:35], v145 offset:15360
	ds_read_b64_tr_b16 v[36:37], v145 offset:16896
	ds_read_b64_tr_b16 v[44:45], v145 offset:16960
	ds_read_b64_tr_b16 v[42:43], v145 offset:15424
	s_cmp_ge_u32 s38, s11
	s_waitcnt lgkmcnt(4)
	v_mfma_f32_32x32x16_bf16 v[18:33], v[50:53], v[38:41], v[18:33]
	v_cvt_pk_bf16_f32 v41, v153, v154
	v_cvt_pk_bf16_f32 v40, v150, v152
	v_cvt_pk_bf16_f32 v39, v148, v149
	v_cvt_pk_bf16_f32 v38, v146, v147
	v_exp_f32_e32 v50, v54
	s_nop 0
	v_add_f32_e32 v234, v50, v234
	s_waitcnt lgkmcnt(2)
	v_mfma_f32_32x32x16_bf16 v[2:17], v[34:37], v[38:41], v[2:17]
	v_exp_f32_e32 v48, v48
	v_exp_f32_e32 v49, v49
	ds_read_b64_tr_b16 v[34:35], v145 offset:18432
	ds_read_b64_tr_b16 v[36:37], v145 offset:19968
	v_add_f32_e32 v234, v55, v234
	v_add_f32_e32 v234, v56, v234
	s_waitcnt lgkmcnt(2)
	v_mfma_f32_32x32x16_bf16 v[18:33], v[42:45], v[38:41], v[18:33]
	ds_read_b64_tr_b16 v[44:45], v145 offset:20032
	ds_read_b64_tr_b16 v[42:43], v145 offset:18496
	v_cvt_pk_bf16_f32 v41, v48, v49
	v_cvt_pk_bf16_f32 v40, v46, v47
	v_cvt_pk_bf16_f32 v39, v55, v56
	v_cvt_pk_bf16_f32 v38, v155, v50
	v_pk_add_f32 v[232:233], v[232:233], v[46:47]
	s_waitcnt lgkmcnt(2)
	v_mfma_f32_32x32x16_bf16 v[2:17], v[34:37], v[38:41], v[2:17]
	v_pk_add_f32 v[232:233], v[232:233], v[48:49]
	v_add_f32_e32 v234, v232, v234
	v_add_f32_e32 v234, v233, v234
	v_add_f32_e32 v101, v101, v234
	s_waitcnt lgkmcnt(0)
	v_mfma_f32_32x32x16_bf16 v[18:33], v[42:45], v[38:41], v[18:33]
	s_cbranch_scc1 .LBB0_2152

.LBB0_4388:
	v_cndmask_b32_e64 v0, v139, v186, s[2:3]
	v_sub_f32_e32 v18, v96, v0
	v_add_u32_e32 v19, s20, v134
	v_exp_f32_e32 v18, v18
	v_add3_u32 v22, v19, v137, v138
	v_sub_f32_e32 v19, v97, v0
	v_exp_f32_e32 v19, v19
	v_sub_f32_e32 v21, v98, v0
	v_exp_f32_e32 v21, v21
	v_sub_f32_e32 v23, v99, v0
	v_exp_f32_e32 v23, v23
	v_sub_f32_e32 v24, v100, v0
	v_exp_f32_e32 v24, v24
	v_sub_f32_e32 v25, v101, v0
	v_pk_add_f32 v[234:235], v[18:19], 0 op_sel_hi:[1,0]
	v_exp_f32_e32 v25, v25
	v_sub_f32_e32 v26, v102, v0
	v_mov_b32_e32 v236, v21
	v_exp_f32_e32 v26, v26
	v_sub_f32_e32 v27, v103, v0
	v_add_f32_e32 v236, v23, v236
	v_exp_f32_e32 v27, v27
	v_sub_f32_e32 v28, v104, v0
	v_exp_f32_e32 v28, v28
	v_sub_f32_e32 v29, v105, v0
	v_pk_add_f32 v[234:235], v[234:235], v[24:25]
	v_exp_f32_e32 v29, v29
	v_sub_f32_e32 v30, v106, v0
	v_exp_f32_e32 v30, v30
	v_sub_f32_e32 v31, v107, v0
	v_pk_add_f32 v[234:235], v[234:235], v[26:27]
	v_exp_f32_e32 v31, v31
	v_sub_f32_e32 v96, v108, v0
	v_exp_f32_e32 v96, v96
	v_sub_f32_e32 v97, v109, v0
	v_pk_add_f32 v[234:235], v[234:235], v[28:29]
	v_exp_f32_e32 v97, v97
	v_sub_f32_e32 v98, v110, v0
	v_exp_f32_e32 v98, v98
	v_sub_f32_e32 v99, v111, v0
	v_pk_add_f32 v[234:235], v[234:235], v[30:31]
	v_exp_f32_e32 v99, v99
	v_sub_f32_e32 v2, v2, v0
	v_exp_f32_e32 v100, v2
	v_sub_f32_e32 v3, v3, v0
	v_pk_add_f32 v[234:235], v[234:235], v[96:97]
	v_exp_f32_e32 v101, v3
	v_sub_f32_e32 v3, v4, v0
	v_exp_f32_e32 v102, v3
	v_sub_f32_e32 v3, v5, v0
	v_pk_add_f32 v[234:235], v[234:235], v[98:99]
	v_exp_f32_e32 v103, v3
	v_sub_f32_e32 v3, v6, v0
	v_exp_f32_e32 v104, v3
	v_pk_add_f32 v[234:235], v[234:235], v[100:101]
	v_pk_add_f32 v[234:235], v[234:235], v[102:103]
	v_add_f32_e32 v236, v104, v236
	v_sub_f32_e32 v2, v7, v0
	v_exp_f32_e32 v106, v2
	v_sub_f32_e32 v2, v8, v0
	v_exp_f32_e32 v107, v2
	v_sub_f32_e32 v2, v9, v0
	v_sub_f32_e32 v6, v10, v0
	v_exp_f32_e32 v108, v2
	ds_read_b64_tr_b16 v[2:3], v22 offset:9216
	ds_read_b64_tr_b16 v[4:5], v22 offset:10752
	v_exp_f32_e32 v109, v6
	v_cvt_pk_bf16_f32 v7, v21, v23
	v_cvt_pk_bf16_f32 v6, v18, v19
	ds_read_b64_tr_b16 v[20:21], v22 offset:10816
	ds_read_b64_tr_b16 v[18:19], v22 offset:9280
	v_cvt_pk_bf16_f32 v9, v26, v27
	v_cvt_pk_bf16_f32 v8, v24, v25
	v_sub_f32_e32 v10, v12, v0
	v_sub_f32_e32 v24, v11, v0
	s_waitcnt lgkmcnt(2)
	v_mfma_f32_32x32x16_bf16 v[64:79], v[2:5], v[6:9], v[64:79]
	v_pk_add_f32 v[234:235], v[234:235], v[106:107]
	v_pk_add_f32 v[234:235], v[234:235], v[108:109]
	ds_read_b64_tr_b16 v[2:3], v22 offset:12288
	ds_read_b64_tr_b16 v[4:5], v22 offset:13824
	v_exp_f32_e32 v25, v10
	v_sub_f32_e32 v15, v15, v0
	s_waitcnt lgkmcnt(2)
	v_mfma_f32_32x32x16_bf16 v[80:95], v[18:21], v[6:9], v[80:95]
	ds_read_b64_tr_b16 v[20:21], v22 offset:13888
	ds_read_b64_tr_b16 v[18:19], v22 offset:12352
	v_cvt_pk_bf16_f32 v9, v98, v99
	v_cvt_pk_bf16_f32 v8, v96, v97
	v_cvt_pk_bf16_f32 v7, v30, v31
	v_cvt_pk_bf16_f32 v6, v28, v29
	v_exp_f32_e32 v15, v15
	s_add_i32 s15, s15, 64
	s_waitcnt lgkmcnt(2)
	v_mfma_f32_32x32x16_bf16 v[64:79], v[2:5], v[6:9], v[64:79]
	v_sub_f32_e32 v2, v13, v0
	v_exp_f32_e32 v26, v2
	v_sub_f32_e32 v2, v14, v0
	v_exp_f32_e32 v14, v2
	ds_read_b64_tr_b16 v[2:3], v22 offset:15360
	ds_read_b64_tr_b16 v[4:5], v22 offset:16896
	ds_read_b64_tr_b16 v[12:13], v22 offset:16960
	ds_read_b64_tr_b16 v[10:11], v22 offset:15424
	v_lshl_add_u64 v[126:127], v[126:127], 0, s[36:37]
	s_waitcnt lgkmcnt(4)
	v_mfma_f32_32x32x16_bf16 v[80:95], v[18:21], v[6:9], v[80:95]
	v_cvt_pk_bf16_f32 v9, v107, v108
	v_cvt_pk_bf16_f32 v8, v104, v106
	v_cvt_pk_bf16_f32 v7, v102, v103
	v_cvt_pk_bf16_f32 v6, v100, v101
	s_cmp_eq_u32 s9, s12
	v_lshl_add_u64 v[128:129], v[128:129], 0, s[36:37]
	s_waitcnt lgkmcnt(2)
	v_mfma_f32_32x32x16_bf16 v[64:79], v[2:5], v[6:9], v[64:79]
	v_sub_f32_e32 v2, v16, v0
	v_sub_f32_e32 v0, v17, v0
	v_exp_f32_e32 v16, v2
	v_exp_f32_e32 v0, v0
	ds_read_b64_tr_b16 v[2:3], v22 offset:18432
	ds_read_b64_tr_b16 v[4:5], v22 offset:19968
	v_exp_f32_e32 v17, v24
	s_waitcnt lgkmcnt(2)
	v_mfma_f32_32x32x16_bf16 v[80:95], v[10:13], v[6:9], v[80:95]
	ds_read_b64_tr_b16 v[12:13], v22 offset:20032
	ds_read_b64_tr_b16 v[10:11], v22 offset:18496
	v_cvt_pk_bf16_f32 v9, v16, v0
	v_cvt_pk_bf16_f32 v8, v14, v15
	v_cvt_pk_bf16_f32 v7, v25, v26
	v_cvt_pk_bf16_f32 v6, v109, v17
	s_waitcnt lgkmcnt(2)
	s_nop 0
	v_mfma_f32_32x32x16_bf16 v[64:79], v[2:5], v[6:9], v[64:79]
	v_add_f32_e32 v236, v25, v236
	v_add_f32_e32 v236, v26, v236
	v_pk_add_f32 v[234:235], v[234:235], v[14:15]
	v_pk_add_f32 v[234:235], v[234:235], v[16:17]
	v_add_f32_e32 v236, v0, v236
	s_waitcnt lgkmcnt(0)
	v_mfma_f32_32x32x16_bf16 v[80:95], v[10:13], v[6:9], v[80:95]
	v_add_f32_e32 v236, v234, v236
	v_add_f32_e32 v236, v235, v236
	v_add_f32_e32 v189, v189, v236
	s_cbranch_scc1 .LBB0_4391
	s_mov_b64 s[2:3], s[12:13]
	s_branch .LBB0_4382

.LBB0_4403:
	v_exp_f32_e32 v0, v128
	v_exp_f32_e32 v19, v129
	v_exp_f32_e32 v20, v130
	v_add_u32_e32 v18, s11, v196
	v_exp_f32_e32 v21, v131
	v_add3_u32 v22, v18, v198, v199
	v_mov_b32_e32 v236, v0
	v_exp_f32_e32 v23, v132
	v_add_f32_e32 v236, v19, v236
	v_exp_f32_e32 v24, v133
	v_exp_f32_e32 v25, v134
	v_pk_add_f32 v[234:235], v[20:21], 0 op_sel_hi:[1,0]
	v_exp_f32_e32 v26, v135
	v_add_f32_e32 v236, v23, v236
	v_exp_f32_e32 v27, v136
	v_exp_f32_e32 v28, v137
	v_pk_add_f32 v[234:235], v[234:235], v[24:25]
	v_exp_f32_e32 v29, v138
	v_exp_f32_e32 v30, v139
	v_pk_add_f32 v[234:235], v[234:235], v[26:27]
	v_exp_f32_e32 v31, v140
	v_exp_f32_e32 v128, v141
	v_pk_add_f32 v[234:235], v[234:235], v[28:29]
	v_exp_f32_e32 v129, v142
	v_exp_f32_e32 v130, v143
	v_pk_add_f32 v[234:235], v[234:235], v[30:31]
	v_exp_f32_e32 v131, v2
	v_exp_f32_e32 v132, v3
	v_pk_add_f32 v[234:235], v[234:235], v[128:129]
	v_exp_f32_e32 v133, v4
	v_exp_f32_e32 v134, v5
	v_pk_add_f32 v[234:235], v[234:235], v[130:131]
	v_exp_f32_e32 v135, v6
	v_pk_add_f32 v[234:235], v[234:235], v[132:133]
	v_pk_add_f32 v[234:235], v[234:235], v[134:135]
	v_exp_f32_e32 v137, v7
	v_exp_f32_e32 v138, v8
	v_exp_f32_e32 v139, v9
	ds_read_b64_tr_b16 v[2:3], v22 offset:9216
	ds_read_b64_tr_b16 v[4:5], v22 offset:10752
	v_exp_f32_e32 v140, v10
	v_cvt_pk_bf16_f32 v7, v20, v21
	v_cvt_pk_bf16_f32 v6, v0, v19
	ds_read_b64_tr_b16 v[20:21], v22 offset:10816
	ds_read_b64_tr_b16 v[18:19], v22 offset:9280
	v_cvt_pk_bf16_f32 v9, v25, v26
	v_cvt_pk_bf16_f32 v8, v23, v24
	v_mov_b32_e32 v23, v11
	s_waitcnt lgkmcnt(2)
	v_mfma_f32_32x32x16_bf16 v[96:111], v[2:5], v[6:9], v[96:111]
	ds_read_b64_tr_b16 v[2:3], v22 offset:12288
	ds_read_b64_tr_b16 v[4:5], v22 offset:13824
	v_exp_f32_e32 v24, v12
	v_exp_f32_e32 v15, v15
	v_add_f32_e32 v236, v137, v236
	v_pk_add_f32 v[234:235], v[234:235], v[138:139]
	s_waitcnt lgkmcnt(2)
	v_mfma_f32_32x32x16_bf16 v[112:127], v[18:21], v[6:9], v[112:127]
	ds_read_b64_tr_b16 v[20:21], v22 offset:13888
	ds_read_b64_tr_b16 v[18:19], v22 offset:12352
	v_cvt_pk_bf16_f32 v9, v129, v130
	v_cvt_pk_bf16_f32 v8, v31, v128
	v_cvt_pk_bf16_f32 v7, v29, v30
	v_cvt_pk_bf16_f32 v6, v27, v28
	v_add_f32_e32 v236, v140, v236
	s_add_i32 s9, s9, 64
	s_waitcnt lgkmcnt(2)
	v_mfma_f32_32x32x16_bf16 v[96:111], v[2:5], v[6:9], v[96:111]
	v_exp_f32_e32 v25, v13
	v_exp_f32_e32 v14, v14
	ds_read_b64_tr_b16 v[2:3], v22 offset:15360
	ds_read_b64_tr_b16 v[4:5], v22 offset:16896
	ds_read_b64_tr_b16 v[12:13], v22 offset:16960
	ds_read_b64_tr_b16 v[10:11], v22 offset:15424
	s_cmp_ge_u32 s6, s5
	s_waitcnt lgkmcnt(4)
	v_mfma_f32_32x32x16_bf16 v[112:127], v[18:21], v[6:9], v[112:127]
	v_cvt_pk_bf16_f32 v9, v138, v139
	v_cvt_pk_bf16_f32 v8, v135, v137
	v_cvt_pk_bf16_f32 v7, v133, v134
	v_cvt_pk_bf16_f32 v6, v131, v132
	v_exp_f32_e32 v18, v23
	s_nop 0
	v_add_f32_e32 v236, v18, v236
	s_waitcnt lgkmcnt(2)
	v_mfma_f32_32x32x16_bf16 v[96:111], v[2:5], v[6:9], v[96:111]
	v_exp_f32_e32 v16, v16
	v_exp_f32_e32 v17, v17
	ds_read_b64_tr_b16 v[2:3], v22 offset:18432
	ds_read_b64_tr_b16 v[4:5], v22 offset:19968
	v_pk_add_f32 v[234:235], v[234:235], v[24:25]
	s_waitcnt lgkmcnt(2)
	v_mfma_f32_32x32x16_bf16 v[112:127], v[10:13], v[6:9], v[112:127]
	ds_read_b64_tr_b16 v[12:13], v22 offset:20032
	ds_read_b64_tr_b16 v[10:11], v22 offset:18496
	v_cvt_pk_bf16_f32 v9, v16, v17
	v_cvt_pk_bf16_f32 v8, v14, v15
	v_cvt_pk_bf16_f32 v7, v24, v25
	v_cvt_pk_bf16_f32 v6, v140, v18
	v_pk_add_f32 v[234:235], v[234:235], v[14:15]
	s_waitcnt lgkmcnt(2)
	v_mfma_f32_32x32x16_bf16 v[96:111], v[2:5], v[6:9], v[96:111]
	v_pk_add_f32 v[234:235], v[234:235], v[16:17]
	v_add_f32_e32 v236, v234, v236
	v_add_f32_e32 v236, v235, v236
	v_add_f32_e32 v192, v192, v236
	s_waitcnt lgkmcnt(0)
	v_mfma_f32_32x32x16_bf16 v[112:127], v[10:13], v[6:9], v[112:127]
	s_cbranch_scc1 .LBB0_4411
